# attn: K/V LDS staging writes interleaved into the last PV MFMA group
# speedup vs baseline: 1.0103x; 1.0061x over previous
.LBB0_256:
	v_sub_f32_e32 v66, v66, v221
	v_mul_f32_e32 v66, 0x3e0293ee, v66
	v_fmamk_f32 v67, v104, 0x3e0293ee, v66
	v_exp_f32_e32 v223, v67
	v_fmamk_f32 v67, v105, 0x3e0293ee, v66
	v_exp_f32_e32 v224, v67
	v_fmamk_f32 v67, v106, 0x3e0293ee, v66
	v_exp_f32_e32 v225, v67
	v_fmamk_f32 v67, v107, 0x3e0293ee, v66
	v_exp_f32_e32 v226, v67
	v_fmamk_f32 v67, v100, 0x3e0293ee, v66
	v_exp_f32_e32 v227, v67
	v_fmamk_f32 v67, v101, 0x3e0293ee, v66
	v_exp_f32_e32 v228, v67
	v_fmamk_f32 v67, v102, 0x3e0293ee, v66
	v_exp_f32_e32 v229, v67
	v_fmamk_f32 v67, v103, 0x3e0293ee, v66
	v_exp_f32_e32 v230, v67
	v_fmamk_f32 v67, v128, 0x3e0293ee, v66
	v_exp_f32_e32 v231, v67
	v_fmamk_f32 v67, v129, 0x3e0293ee, v66
	v_exp_f32_e32 v232, v67
	v_fmamk_f32 v67, v130, 0x3e0293ee, v66
	v_exp_f32_e32 v233, v67
	v_fmamk_f32 v67, v131, 0x3e0293ee, v66
	v_exp_f32_e32 v234, v67
	v_fmamk_f32 v67, v112, 0x3e0293ee, v66
	v_exp_f32_e32 v235, v67
	v_fmamk_f32 v67, v113, 0x3e0293ee, v66
	v_exp_f32_e32 v236, v67
	v_fmamk_f32 v67, v114, 0x3e0293ee, v66
	v_fmac_f32_e32 v66, 0x3e0293ee, v115
	v_exp_f32_e32 v237, v67
	v_exp_f32_e32 v238, v66
	s_waitcnt lgkmcnt(0)
	s_add_i32 s8, s0, 2
	v_cvt_pk_bf16_f32 v104, v223, v224
	v_cvt_pk_bf16_f32 v105, v225, v226
	v_cvt_pk_bf16_f32 v106, v227, v228
	v_cvt_pk_bf16_f32 v107, v229, v230
	v_cvt_pk_bf16_f32 v100, v231, v232
	v_cvt_pk_bf16_f32 v101, v233, v234
	v_cvt_pk_bf16_f32 v102, v235, v236
	v_cvt_pk_bf16_f32 v103, v237, v238
	v_mfma_f32_16x16x32_bf16 v[96:99], v[116:119], v[104:107], v[96:99]
	s_nop 0
	v_mfma_f32_16x16x32_bf16 v[96:99], v[108:111], v[100:103], v[96:99]
	ds_read_b64_tr_b16 v[108:109], v218 offset:0
	ds_read_b64_tr_b16 v[110:111], v218 offset:8192
	ds_read_b64_tr_b16 v[112:113], v218 offset:16384
	ds_read_b64_tr_b16 v[114:115], v218 offset:24576
	v_mfma_f32_16x16x32_bf16 v[88:91], v[120:123], v[104:107], v[88:91]
	ds_read_b64_tr_b16 v[116:117], v219 offset:0
	ds_read_b64_tr_b16 v[118:119], v219 offset:8192
	ds_read_b64_tr_b16 v[120:121], v219 offset:16384
	ds_read_b64_tr_b16 v[122:123], v219 offset:24576
	v_mfma_f32_16x16x32_bf16 v[80:83], v[136:139], v[104:107], v[80:83]
	v_mfma_f32_16x16x32_bf16 v[88:91], v[124:127], v[100:103], v[88:91]
	ds_read_b64_tr_b16 v[124:125], v220 offset:0
	ds_read_b64_tr_b16 v[126:127], v220 offset:8192
	ds_read_b64_tr_b16 v[128:129], v220 offset:16384
	v_mfma_f32_16x16x32_bf16 v[72:75], v[140:143], v[104:107], v[72:75]
	ds_read_b64_tr_b16 v[130:131], v220 offset:24576
	v_mfma_f32_16x16x32_bf16 v[80:83], v[132:135], v[100:103], v[80:83]
	ds_read_b64_tr_b16 v[132:133], v171 offset:0
	ds_read_b64_tr_b16 v[134:135], v171 offset:8192
	ds_read_b64_tr_b16 v[136:137], v171 offset:16384
	v_mfma_f32_16x16x32_bf16 v[72:75], v[144:147], v[100:103], v[72:75]
	ds_read_b64_tr_b16 v[138:139], v171 offset:24576
	s_waitcnt lgkmcnt(0)
	v_mfma_f32_16x16x32_bf16 v[56:59], v[108:111], v[104:107], v[56:59]
	ds_read_b64_tr_b16 v[108:109], v172 offset:256
	ds_read_b64_tr_b16 v[110:111], v172 offset:8448
	v_mfma_f32_16x16x32_bf16 v[48:51], v[116:119], v[104:107], v[48:51]
	v_mfma_f32_16x16x32_bf16 v[56:59], v[112:115], v[100:103], v[56:59]
	ds_read_b64_tr_b16 v[112:113], v172 offset:16640
	ds_read_b64_tr_b16 v[114:115], v172 offset:24832
	ds_read_b64_tr_b16 v[116:117], v175 offset:256
	ds_read_b64_tr_b16 v[118:119], v175 offset:8448
	v_mfma_f32_16x16x32_bf16 v[40:43], v[124:127], v[104:107], v[40:43]
	v_mfma_f32_16x16x32_bf16 v[48:51], v[120:123], v[100:103], v[48:51]
	ds_read_b64_tr_b16 v[120:121], v175 offset:16640
	ds_read_b64_tr_b16 v[122:123], v175 offset:24832
	ds_read_b64_tr_b16 v[124:125], v176 offset:256
	ds_read_b64_tr_b16 v[126:127], v176 offset:8448
	v_mfma_f32_16x16x32_bf16 v[32:35], v[132:135], v[104:107], v[32:35]
	v_mfma_f32_16x16x32_bf16 v[40:43], v[128:131], v[100:103], v[40:43]
	ds_read_b64_tr_b16 v[128:129], v176 offset:16640
	ds_read_b64_tr_b16 v[130:131], v176 offset:24832
	ds_read_b64_tr_b16 v[132:133], v181 offset:256
	ds_read_b64_tr_b16 v[134:135], v181 offset:8448
	v_mfma_f32_16x16x32_bf16 v[32:35], v[136:139], v[100:103], v[32:35]
	ds_read_b64_tr_b16 v[136:137], v181 offset:16640
	ds_read_b64_tr_b16 v[138:139], v181 offset:24832
	s_waitcnt lgkmcnt(0)
	v_mfma_f32_16x16x32_bf16 v[92:95], v[108:111], v[104:107], v[92:95]
	ds_read_b64_tr_b16 v[108:109], v218 offset:256
	ds_read_b64_tr_b16 v[110:111], v218 offset:8448
	v_mfma_f32_16x16x32_bf16 v[84:87], v[116:119], v[104:107], v[84:87]
	v_mfma_f32_16x16x32_bf16 v[92:95], v[112:115], v[100:103], v[92:95]
	ds_read_b64_tr_b16 v[112:113], v218 offset:16640
	ds_read_b64_tr_b16 v[114:115], v218 offset:24832
	ds_read_b64_tr_b16 v[116:117], v219 offset:256
	ds_read_b64_tr_b16 v[118:119], v219 offset:8448
	v_mfma_f32_16x16x32_bf16 v[76:79], v[124:127], v[104:107], v[76:79]
	v_mfma_f32_16x16x32_bf16 v[84:87], v[120:123], v[100:103], v[84:87]
	ds_read_b64_tr_b16 v[120:121], v219 offset:16640
	ds_read_b64_tr_b16 v[122:123], v219 offset:24832
	ds_read_b64_tr_b16 v[124:125], v220 offset:256
	ds_read_b64_tr_b16 v[126:127], v220 offset:8448
	v_mfma_f32_16x16x32_bf16 v[66:69], v[132:135], v[104:107], v[68:71]
	v_mfma_f32_16x16x32_bf16 v[76:79], v[128:131], v[100:103], v[76:79]
	ds_read_b64_tr_b16 v[128:129], v220 offset:16640
	ds_read_b64_tr_b16 v[130:131], v220 offset:24832
	ds_read_b64_tr_b16 v[132:133], v171 offset:256
	ds_read_b64_tr_b16 v[134:135], v171 offset:8448
	v_mfma_f32_16x16x32_bf16 v[66:69], v[136:139], v[100:103], v[66:69]
	ds_read_b64_tr_b16 v[136:137], v171 offset:16640
	ds_read_b64_tr_b16 v[138:139], v171 offset:24832
	s_waitcnt lgkmcnt(0)
	v_mfma_f32_16x16x32_bf16 v[60:63], v[108:111], v[104:107], v[60:63]
	s_waitcnt vmcnt(6)
	ds_write_b128 v166, v[16:19] offset:17408
	v_mfma_f32_16x16x32_bf16 v[52:55], v[116:119], v[104:107], v[52:55]
	ds_write_b128 v167, v[20:23] offset:17408
	v_mfma_f32_16x16x32_bf16 v[44:47], v[124:127], v[104:107], v[44:47]
	ds_write_b128 v169, v[194:197] offset:36864
	v_mfma_f32_16x16x32_bf16 v[36:39], v[132:135], v[104:107], v[36:39]
	ds_write_b128 v169, v[198:201] offset:45056
	v_mfma_f32_16x16x32_bf16 v[60:63], v[112:115], v[100:103], v[60:63]
	ds_write_b128 v169, v[202:205] offset:53248
	v_mfma_f32_16x16x32_bf16 v[52:55], v[120:123], v[100:103], v[52:55]
	ds_write_b128 v169, v[242:245] offset:61440
	v_mfma_f32_16x16x32_bf16 v[44:47], v[128:131], v[100:103], v[44:47]
	v_mfma_f32_16x16x32_bf16 v[36:39], v[136:139], v[100:103], v[36:39]
	s_min_u32 s9, s8, 28
	s_lshl_b32 s9, s9, 6
	s_addk_i32 s9, 0xc0
	s_mul_i32 s29, s9, 0xa080
	s_add_u32 s72, s24, s29
	s_addc_u32 s73, s25, 0
	s_add_u32 s74, s26, s29
	s_addc_u32 s75, s27, 0
	s_add_u32 s76, s74, 0xa0800
	s_addc_u32 s77, s75, 0
	s_add_u32 s78, s76, 0xa0800
	s_addc_u32 s79, s77, 0
	s_add_u32 s80, s78, 0xa0800
	s_addc_u32 s81, s79, 0
	s_waitcnt lgkmcnt(0)
	s_barrier
	ds_read_b128 v[100:103], v191 offset:0
	ds_read_b128 v[104:107], v191 offset:64
	ds_read_b128 v[108:111], v191 offset:0x80
	ds_read_b128 v[112:115], v191 offset:0xc0
	ds_read_b128 v[116:119], v191 offset:0x1100
	ds_read_b128 v[120:123], v191 offset:0x1140
	ds_read_b128 v[124:127], v191 offset:0x1180
	ds_read_b128 v[128:131], v191 offset:0x11c0
	global_load_dwordx4 v[194:197], v239, s[74:75]
	global_load_dwordx4 v[198:201], v239, s[76:77]
	global_load_dwordx4 v[202:205], v239, s[78:79]
	global_load_dwordx4 v[242:245], v239, s[80:81]
	global_load_dwordx4 v[16:19], v246, s[72:73]
	global_load_dwordx4 v[20:23], v247, s[72:73]
	s_waitcnt lgkmcnt(0)
	s_nop 0
	v_mfma_f32_16x16x32_bf16 v[100:103], v[100:103], v[8:11], 0
	v_mfma_f32_16x16x32_bf16 v[116:119], v[116:119], v[8:11], 0
	v_mfma_f32_16x16x32_bf16 v[100:103], v[104:107], v[0:3], v[100:103]
	v_mfma_f32_16x16x32_bf16 v[104:107], v[120:123], v[0:3], v[116:119]
	v_mfma_f32_16x16x32_bf16 v[100:103], v[108:111], v[4:7], v[100:103]
	v_mfma_f32_16x16x32_bf16 v[104:107], v[124:127], v[4:7], v[104:107]
	v_mfma_f32_16x16x32_bf16 v[112:115], v[112:115], v[12:15], v[100:103]
	v_mfma_f32_16x16x32_bf16 v[100:103], v[128:131], v[12:15], v[104:107]
	ds_read_b128 v[104:107], v191 offset:0x2200
	ds_read_b128 v[108:111], v191 offset:0x2240
	ds_read_b128 v[116:119], v191 offset:0x2280
	ds_read_b128 v[120:123], v191 offset:0x22c0
	ds_read_b128 v[124:127], v191 offset:0x3300
	ds_read_b128 v[128:131], v191 offset:0x3340
	ds_read_b128 v[132:135], v191 offset:0x3380
	ds_read_b128 v[136:139], v191 offset:0x33c0
	s_waitcnt lgkmcnt(0)
	s_nop 5
	v_mfma_f32_16x16x32_bf16 v[104:107], v[104:107], v[8:11], 0
	s_add_i32 s9, s17, 0xffffff96
	s_cmp_lt_u32 s9, 0xfffffefd
	v_mfma_f32_16x16x32_bf16 v[104:107], v[108:111], v[0:3], v[104:107]
	v_mfma_f32_16x16x32_bf16 v[124:127], v[124:127], v[8:11], 0
	v_mfma_f32_16x16x32_bf16 v[104:107], v[116:119], v[4:7], v[104:107]
	ds_read_b64_tr_b16 v[116:117], v172 offset:36864
	ds_read_b64_tr_b16 v[118:119], v172 offset:45056
	v_mfma_f32_16x16x32_bf16 v[108:111], v[128:131], v[0:3], v[124:127]
	v_mfma_f32_16x16x32_bf16 v[128:131], v[120:123], v[12:15], v[104:107]
	ds_read_b64_tr_b16 v[104:105], v172 offset:53248
	ds_read_b64_tr_b16 v[106:107], v172 offset:61440
	ds_read_b64_tr_b16 v[120:121], v175 offset:36864
	v_mfma_f32_16x16x32_bf16 v[108:111], v[132:135], v[4:7], v[108:111]
	ds_read_b64_tr_b16 v[122:123], v175 offset:45056
	ds_read_b64_tr_b16 v[124:125], v175 offset:53248
	ds_read_b64_tr_b16 v[126:127], v175 offset:61440
	v_mfma_f32_16x16x32_bf16 v[108:111], v[136:139], v[12:15], v[108:111]
	ds_read_b64_tr_b16 v[136:137], v176 offset:36864
	ds_read_b64_tr_b16 v[138:139], v176 offset:45056
	ds_read_b64_tr_b16 v[132:133], v176 offset:53248
	ds_read_b64_tr_b16 v[134:135], v176 offset:61440
	ds_read_b64_tr_b16 v[140:141], v181 offset:36864
	ds_read_b64_tr_b16 v[142:143], v181 offset:45056
	ds_read_b64_tr_b16 v[144:145], v181 offset:53248
	ds_read_b64_tr_b16 v[146:147], v181 offset:61440
	s_cbranch_scc1 .LBB0_258
	v_add_u32_e32 v70, s17, v193
	v_add_u32_e32 v152, 0x80, v70
	v_max_i32_e32 v71, -1, v152
	v_add_u32_e32 v71, 1, v71
	v_med3_i32 v70, v152, 0, v188
	s_add_i32 s9, 0, 0x1a800
	v_min_u32_e32 v71, 0x100, v71
	v_lshl_add_u32 v70, v70, 2, s9
	v_lshl_add_u32 v71, v71, 2, s9
	ds_read_b32 v70, v70
	ds_read_b32 v71, v71
	v_max_i32_e32 v153, -2, v152
	v_add_u32_e32 v153, 2, v153
	v_min_u32_e32 v153, 0x100, v153
	v_lshl_add_u32 v153, v153, 2, s9
	ds_read_b32 v240, v153
	v_max_i32_e32 v153, -3, v152
	s_waitcnt lgkmcnt(1)
	v_pk_add_f32 v[112:113], v[112:113], v[70:71]
	v_max_i32_e32 v70, -16, v152
	v_max_i32_e32 v71, 0xffffffef, v152
	v_add_u32_e32 v153, 3, v153
	v_add_u32_e32 v70, 16, v70
	v_add_u32_e32 v71, 17, v71
	v_min_u32_e32 v153, 0x100, v153
	v_min_u32_e32 v70, 0x100, v70
	v_min_u32_e32 v71, 0x100, v71
	v_lshl_add_u32 v153, v153, 2, s9
	v_lshl_add_u32 v70, v70, 2, s9
	v_lshl_add_u32 v71, v71, 2, s9
	ds_read_b32 v241, v153
	ds_read_b32 v70, v70
	ds_read_b32 v71, v71
	v_max_i32_e32 v153, 0xffffffee, v152
	v_add_u32_e32 v153, 18, v153
	v_min_u32_e32 v153, 0x100, v153
	v_lshl_add_u32 v153, v153, 2, s9
	s_waitcnt lgkmcnt(0)
	v_pk_add_f32 v[100:101], v[100:101], v[70:71]
	v_max_i32_e32 v70, 0xffffffe0, v152
	v_max_i32_e32 v71, 0xffffffdf, v152
	v_add_u32_e32 v70, 32, v70
	v_add_u32_e32 v71, 33, v71
	v_min_u32_e32 v70, 0x100, v70
	v_min_u32_e32 v71, 0x100, v71
	v_lshl_add_u32 v70, v70, 2, s9
	v_lshl_add_u32 v71, v71, 2, s9
	v_pk_add_f32 v[114:115], v[114:115], v[240:241]
	ds_read_b32 v240, v153
	ds_read_b32 v70, v70
	ds_read_b32 v71, v71
	v_max_i32_e32 v153, 0xffffffed, v152
	v_add_u32_e32 v153, 19, v153
	v_min_u32_e32 v153, 0x100, v153
	v_lshl_add_u32 v153, v153, 2, s9
	ds_read_b32 v241, v153
	v_max_i32_e32 v153, 0xffffffde, v152
	v_add_u32_e32 v153, 34, v153
	v_min_u32_e32 v153, 0x100, v153
	v_lshl_add_u32 v153, v153, 2, s9
	s_waitcnt lgkmcnt(0)
	v_pk_add_f32 v[102:103], v[102:103], v[240:241]
	ds_read_b32 v240, v153
	v_max_i32_e32 v153, 0xffffffdd, v152
	v_add_u32_e32 v153, 35, v153
	v_min_u32_e32 v153, 0x100, v153
	v_lshl_add_u32 v153, v153, 2, s9
	ds_read_b32 v241, v153
	v_pk_add_f32 v[128:129], v[128:129], v[70:71]
	v_max_i32_e32 v70, 0xffffffd0, v152
	v_max_i32_e32 v71, 0xffffffcf, v152
	v_max_i32_e32 v153, 0xffffffce, v152
	v_max_i32_e32 v152, 0xffffffcd, v152
	v_add_u32_e32 v70, 48, v70
	v_add_u32_e32 v71, 49, v71
	v_add_u32_e32 v153, 50, v153
	v_add_u32_e32 v152, 51, v152
	v_min_u32_e32 v70, 0x100, v70
	v_min_u32_e32 v71, 0x100, v71
	v_min_u32_e32 v153, 0x100, v153
	v_min_u32_e32 v152, 0x100, v152
	v_lshl_add_u32 v70, v70, 2, s9
	v_lshl_add_u32 v71, v71, 2, s9
	v_lshl_add_u32 v153, v153, 2, s9
	v_lshl_add_u32 v152, v152, 2, s9
	s_waitcnt lgkmcnt(0)
	v_pk_add_f32 v[130:131], v[130:131], v[240:241]
	ds_read_b32 v70, v70
	ds_read_b32 v71, v71
	ds_read_b32 v240, v153
	ds_read_b32 v241, v152
	s_waitcnt lgkmcnt(2)
	v_pk_add_f32 v[108:109], v[108:109], v[70:71]
	s_waitcnt lgkmcnt(0)
	v_pk_add_f32 v[110:111], v[110:111], v[240:241]

.LBB0_260:
	v_sub_f32_e32 v70, v70, v221
	v_mul_f32_e32 v70, 0x3e0293ee, v70
	v_fmamk_f32 v71, v112, 0x3e0293ee, v70
	v_exp_f32_e32 v71, v71
	v_fmamk_f32 v112, v113, 0x3e0293ee, v70
	v_exp_f32_e32 v112, v112
	v_fmamk_f32 v113, v114, 0x3e0293ee, v70
	v_exp_f32_e32 v113, v113
	v_fmamk_f32 v114, v115, 0x3e0293ee, v70
	v_exp_f32_e32 v114, v114
	v_fmamk_f32 v100, v100, 0x3e0293ee, v70
	v_add_f32_e32 v115, 0, v71
	v_exp_f32_e32 v100, v100
	v_fmamk_f32 v101, v101, 0x3e0293ee, v70
	v_add_f32_e32 v115, v112, v115
	v_exp_f32_e32 v101, v101
	v_fmamk_f32 v102, v102, 0x3e0293ee, v70
	v_add_f32_e32 v115, v113, v115
	v_exp_f32_e32 v102, v102
	v_fmamk_f32 v103, v103, 0x3e0293ee, v70
	v_add_f32_e32 v115, v114, v115
	v_exp_f32_e32 v103, v103
	v_fmamk_f32 v128, v128, 0x3e0293ee, v70
	v_add_f32_e32 v115, v100, v115
	v_exp_f32_e32 v128, v128
	v_fmamk_f32 v129, v129, 0x3e0293ee, v70
	v_fmamk_f32 v108, v108, 0x3e0293ee, v70
	v_add_f32_e32 v115, v101, v115
	v_exp_f32_e32 v129, v129
	v_fmamk_f32 v130, v130, 0x3e0293ee, v70
	v_exp_f32_e32 v153, v108
	v_fmamk_f32 v108, v109, 0x3e0293ee, v70
	v_add_f32_e32 v115, v102, v115
	v_exp_f32_e32 v130, v130
	v_fmamk_f32 v131, v131, 0x3e0293ee, v70
	v_exp_f32_e32 v223, v108
	v_fmamk_f32 v108, v110, 0x3e0293ee, v70
	v_fmac_f32_e32 v70, 0x3e0293ee, v111
	v_add_f32_e32 v115, v103, v115
	v_exp_f32_e32 v131, v131
	v_exp_f32_e32 v224, v108
	v_exp_f32_e32 v225, v70
	v_add_f32_e32 v115, v128, v115
	s_waitcnt lgkmcnt(0)
	v_add_f32_e32 v115, v129, v115
	v_add_f32_e32 v115, v130, v115
	s_add_i32 s0, s0, 3
	v_add_f32_e32 v152, v131, v115
	v_cvt_pk_bf16_f32 v108, v71, v112
	v_cvt_pk_bf16_f32 v109, v113, v114
	v_cvt_pk_bf16_f32 v110, v100, v101
	v_cvt_pk_bf16_f32 v111, v102, v103
	v_cvt_pk_bf16_f32 v100, v128, v129
	v_cvt_pk_bf16_f32 v101, v130, v131
	v_cvt_pk_bf16_f32 v102, v153, v223
	v_cvt_pk_bf16_f32 v103, v224, v225
	v_mfma_f32_16x16x32_bf16 v[96:99], v[116:119], v[108:111], v[96:99]
	s_nop 0
	v_mfma_f32_16x16x32_bf16 v[96:99], v[104:107], v[100:103], v[96:99]
	ds_read_b64_tr_b16 v[104:105], v218 offset:36864
	ds_read_b64_tr_b16 v[106:107], v218 offset:45056
	ds_read_b64_tr_b16 v[112:113], v218 offset:53248
	ds_read_b64_tr_b16 v[114:115], v218 offset:61440
	v_mfma_f32_16x16x32_bf16 v[88:91], v[120:123], v[108:111], v[88:91]
	ds_read_b64_tr_b16 v[116:117], v219 offset:36864
	ds_read_b64_tr_b16 v[118:119], v219 offset:45056
	ds_read_b64_tr_b16 v[120:121], v219 offset:53248
	ds_read_b64_tr_b16 v[122:123], v219 offset:61440
	v_mfma_f32_16x16x32_bf16 v[80:83], v[136:139], v[108:111], v[80:83]
	v_mfma_f32_16x16x32_bf16 v[88:91], v[124:127], v[100:103], v[88:91]
	ds_read_b64_tr_b16 v[124:125], v220 offset:36864
	ds_read_b64_tr_b16 v[126:127], v220 offset:45056
	ds_read_b64_tr_b16 v[128:129], v220 offset:53248
	v_mfma_f32_16x16x32_bf16 v[70:73], v[140:143], v[108:111], v[72:75]
	ds_read_b64_tr_b16 v[130:131], v220 offset:61440
	v_mfma_f32_16x16x32_bf16 v[80:83], v[132:135], v[100:103], v[80:83]
	ds_read_b64_tr_b16 v[132:133], v171 offset:36864
	ds_read_b64_tr_b16 v[134:135], v171 offset:45056
	ds_read_b64_tr_b16 v[136:137], v171 offset:53248
	v_mfma_f32_16x16x32_bf16 v[72:75], v[144:147], v[100:103], v[70:73]
	ds_read_b64_tr_b16 v[138:139], v171 offset:61440
	s_waitcnt lgkmcnt(0)
	v_mfma_f32_16x16x32_bf16 v[56:59], v[104:107], v[108:111], v[56:59]
	ds_read_b64_tr_b16 v[104:105], v172 offset:37120
	ds_read_b64_tr_b16 v[106:107], v172 offset:45312
	v_mfma_f32_16x16x32_bf16 v[48:51], v[116:119], v[108:111], v[48:51]
	v_mfma_f32_16x16x32_bf16 v[56:59], v[112:115], v[100:103], v[56:59]
	ds_read_b64_tr_b16 v[112:113], v172 offset:53504
	ds_read_b64_tr_b16 v[114:115], v172 offset:61696
	ds_read_b64_tr_b16 v[116:117], v175 offset:37120
	ds_read_b64_tr_b16 v[118:119], v175 offset:45312
	v_mfma_f32_16x16x32_bf16 v[40:43], v[124:127], v[108:111], v[40:43]
	v_mfma_f32_16x16x32_bf16 v[48:51], v[120:123], v[100:103], v[48:51]
	ds_read_b64_tr_b16 v[120:121], v175 offset:53504
	ds_read_b64_tr_b16 v[122:123], v175 offset:61696
	ds_read_b64_tr_b16 v[124:125], v176 offset:37120
	ds_read_b64_tr_b16 v[126:127], v176 offset:45312
	v_mfma_f32_16x16x32_bf16 v[32:35], v[132:135], v[108:111], v[32:35]
	v_mfma_f32_16x16x32_bf16 v[40:43], v[128:131], v[100:103], v[40:43]
	ds_read_b64_tr_b16 v[128:129], v176 offset:53504
	ds_read_b64_tr_b16 v[130:131], v176 offset:61696
	ds_read_b64_tr_b16 v[132:133], v181 offset:37120
	ds_read_b64_tr_b16 v[134:135], v181 offset:45312
	v_mfma_f32_16x16x32_bf16 v[32:35], v[136:139], v[100:103], v[32:35]
	ds_read_b64_tr_b16 v[136:137], v181 offset:53504
	ds_read_b64_tr_b16 v[138:139], v181 offset:61696
	s_waitcnt lgkmcnt(0)
	v_mfma_f32_16x16x32_bf16 v[92:95], v[104:107], v[108:111], v[92:95]
	ds_read_b64_tr_b16 v[104:105], v218 offset:37120
	ds_read_b64_tr_b16 v[106:107], v218 offset:45312
	v_mfma_f32_16x16x32_bf16 v[84:87], v[116:119], v[108:111], v[84:87]
	v_mfma_f32_16x16x32_bf16 v[92:95], v[112:115], v[100:103], v[92:95]
	ds_read_b64_tr_b16 v[112:113], v218 offset:53504
	ds_read_b64_tr_b16 v[114:115], v218 offset:61696
	ds_read_b64_tr_b16 v[116:117], v219 offset:37120
	ds_read_b64_tr_b16 v[118:119], v219 offset:45312
	v_mfma_f32_16x16x32_bf16 v[76:79], v[124:127], v[108:111], v[76:79]
	v_mfma_f32_16x16x32_bf16 v[84:87], v[120:123], v[100:103], v[84:87]
	ds_read_b64_tr_b16 v[120:121], v219 offset:53504
	ds_read_b64_tr_b16 v[122:123], v219 offset:61696
	ds_read_b64_tr_b16 v[124:125], v220 offset:37120
	ds_read_b64_tr_b16 v[126:127], v220 offset:45312
	v_mfma_f32_16x16x32_bf16 v[66:69], v[132:135], v[108:111], v[66:69]
	v_mfma_f32_16x16x32_bf16 v[76:79], v[128:131], v[100:103], v[76:79]
	ds_read_b64_tr_b16 v[128:129], v220 offset:53504
	ds_read_b64_tr_b16 v[130:131], v220 offset:61696
	ds_read_b64_tr_b16 v[132:133], v171 offset:37120
	ds_read_b64_tr_b16 v[134:135], v171 offset:45312
	v_mfma_f32_16x16x32_bf16 v[68:71], v[136:139], v[100:103], v[66:69]
	ds_read_b64_tr_b16 v[136:137], v171 offset:53504
	ds_read_b64_tr_b16 v[138:139], v171 offset:61696
	s_waitcnt lgkmcnt(0)
	v_mfma_f32_16x16x32_bf16 v[60:63], v[104:107], v[108:111], v[60:63]
	s_waitcnt vmcnt(6)
	ds_write_b128 v166, v[24:27]
	v_mfma_f32_16x16x32_bf16 v[52:55], v[116:119], v[108:111], v[52:55]
	ds_write_b128 v167, v[28:31]
	v_mfma_f32_16x16x32_bf16 v[44:47], v[124:127], v[108:111], v[44:47]
	ds_write_b128 v169, v[206:209] offset:0
	v_mfma_f32_16x16x32_bf16 v[36:39], v[132:135], v[108:111], v[36:39]
	ds_write_b128 v169, v[210:213] offset:8192
	v_mfma_f32_16x16x32_bf16 v[60:63], v[112:115], v[100:103], v[60:63]
	ds_write_b128 v169, v[214:217] offset:16384
	v_mfma_f32_16x16x32_bf16 v[52:55], v[120:123], v[100:103], v[52:55]
	ds_write_b128 v169, v[248:251] offset:24576
	v_mfma_f32_16x16x32_bf16 v[44:47], v[128:131], v[100:103], v[44:47]
	v_mfma_f32_16x16x32_bf16 v[36:39], v[136:139], v[100:103], v[36:39]
	v_add_f32_e32 v24, v153, v152
	v_add_f32_e32 v24, v223, v24
	v_add_f32_e32 v24, v224, v24
	v_add_f32_e32 v66, v225, v24
	s_min_u32 s0, s0, 28
	s_waitcnt lgkmcnt(0)
	s_barrier
	s_lshl_b32 s0, s0, 6
	s_addk_i32 s0, 0xc0
	s_mul_i32 s29, s0, 0xa080
	s_add_u32 s72, s24, s29
	s_addc_u32 s73, s25, 0
	s_add_u32 s74, s26, s29
	s_addc_u32 s75, s27, 0
	s_add_u32 s76, s74, 0xa0800
	s_addc_u32 s77, s75, 0
	s_add_u32 s78, s76, 0xa0800
	s_addc_u32 s79, s77, 0
	s_add_u32 s80, s78, 0xa0800
	s_addc_u32 s81, s79, 0
	s_addk_i32 s17, 0x80
	s_cmp_lt_u32 s8, 30
	v_add_f32_e32 v222, v222, v66
	s_cbranch_scc0 .LBB0_248
	s_mov_b32 s0, s8
	s_branch .LBB0_252
